# v19: v17 + l0 q/kv up-projection small-GEMM phase with write-through stores and no L2 write-back at its barrier
# baseline (speedup 1.0000x reference)
.LBB0_715:
	s_mul_hi_i32 s2, s22, 0x2aaaaaab
	s_lshr_b32 s3, s2, 31
	s_ashr_i32 s2, s2, 3
	s_add_i32 s12, s2, s3
	s_mul_i32 s2, s12, 0xffffe800
	s_add_i32 s2, s27, s2
	s_ashr_i32 s3, s2, 31
	s_lshl_b32 s12, s12, 7
	s_ashr_i32 s13, s12, 31
	s_lshl_b64 s[48:49], s[2:3], 9
	s_add_u32 s48, s23, s48
	s_addc_u32 s49, s24, s49
	s_lshl_b64 s[50:51], s[12:13], 9
	s_add_u32 s50, s25, s50
	v_lshl_add_u64 v[2:3], s[48:49], 0, v[34:35]
	s_mov_b32 m0, s29
	s_addc_u32 s51, s26, s51
	v_lshl_add_u64 v[40:41], v[2:3], 0, v[36:37]
	v_lshl_add_u64 v[2:3], s[48:49], 0, v[38:39]
	global_load_lds_dwordx4 v[40:41], off
	v_lshl_add_u64 v[88:89], v[2:3], 0, v[36:37]
	s_mov_b32 m0, s34
	v_lshl_add_u64 v[2:3], s[50:51], 0, v[34:35]
	global_load_lds_dwordx4 v[88:89], off
	v_lshl_add_u64 v[90:91], v[2:3], 0, v[36:37]
	s_mov_b32 m0, s35
	v_lshl_add_u64 v[2:3], s[50:51], 0, v[38:39]
	global_load_lds_dwordx4 v[90:91], off
	v_lshl_add_u64 v[92:93], v[2:3], 0, v[36:37]
	s_mov_b32 m0, s36
	v_lshl_add_u64 v[2:3], v[40:41], 0, s[6:7]
	global_load_lds_dwordx4 v[92:93], off
	s_mov_b32 m0, s37
	v_add_u32_e32 v59, s2, v46
	global_load_lds_dwordx4 v[2:3], off
	v_lshl_add_u64 v[2:3], v[88:89], 0, s[6:7]
	s_mov_b32 m0, s38
	s_nop 0
	global_load_lds_dwordx4 v[2:3], off
	v_lshl_add_u64 v[2:3], v[90:91], 0, s[6:7]
	s_mov_b32 m0, s39
	s_nop 0
	global_load_lds_dwordx4 v[2:3], off
	v_lshl_add_u64 v[2:3], v[92:93], 0, s[6:7]
	s_mov_b32 m0, s40
	s_nop 0
	global_load_lds_dwordx4 v[2:3], off
	v_lshl_add_u64 v[2:3], v[40:41], 0, s[8:9]
	s_mov_b32 m0, s41
	s_nop 0
	global_load_lds_dwordx4 v[2:3], off
	v_lshl_add_u64 v[2:3], v[88:89], 0, s[8:9]
	s_mov_b32 m0, s42
	s_nop 0
	global_load_lds_dwordx4 v[2:3], off
	v_lshl_add_u64 v[2:3], v[90:91], 0, s[8:9]
	s_mov_b32 m0, s43
	s_nop 0
	global_load_lds_dwordx4 v[2:3], off
	v_lshl_add_u64 v[2:3], v[92:93], 0, s[8:9]
	s_mov_b32 m0, s44
	s_nop 0
	global_load_lds_dwordx4 v[2:3], off
	s_waitcnt vmcnt(8)
	s_barrier
	ds_read_b128 v[2:5], v57 offset:17408
	ds_read_b128 v[6:9], v47 offset:1024
	ds_read_b128 v[10:13], v47 offset:2048
	ds_read_b128 v[14:17], v57 offset:18432
	ds_read_b128 v[22:25], v57 offset:19456
	ds_read_b128 v[26:29], v57 offset:20480
	ds_read_b128 v[30:33], v47 offset:3072
	ds_read_b128 v[60:63], v47 offset:4096
	ds_read_b128 v[68:71], v47 offset:5120
	ds_read_b128 v[72:75], v47 offset:6144
	ds_read_b128 v[80:83], v47 offset:7168
	ds_read_b128 v[84:87], v47 offset:8192
	s_waitcnt lgkmcnt(0)
	v_mfma_f32_16x16x32_bf16 v[18:21], v[2:5], v[6:9], 0
	s_waitcnt lgkmcnt(0)
	s_barrier
	v_mfma_f32_16x16x32_bf16 v[6:9], v[22:25], v[6:9], 0
	s_mov_b32 m0, s29
	v_mfma_f32_16x16x32_bf16 v[64:67], v[2:5], v[30:33], 0
	v_mfma_f32_16x16x32_bf16 v[30:33], v[22:25], v[30:33], 0
	v_mfma_f32_16x16x32_bf16 v[76:79], v[2:5], v[68:71], 0
	v_mfma_f32_16x16x32_bf16 v[2:5], v[2:5], v[80:83], 0
	v_mfma_f32_16x16x32_bf16 v[18:21], v[14:17], v[10:13], v[18:21]
	v_mfma_f32_16x16x32_bf16 v[6:9], v[26:29], v[10:13], v[6:9]
	v_mfma_f32_16x16x32_bf16 v[10:13], v[14:17], v[60:63], v[64:67]
	v_mfma_f32_16x16x32_bf16 v[30:33], v[26:29], v[60:63], v[30:33]
	v_mfma_f32_16x16x32_bf16 v[60:63], v[14:17], v[72:75], v[76:79]
	v_mfma_f32_16x16x32_bf16 v[2:5], v[14:17], v[84:87], v[2:5]
	v_lshl_add_u64 v[14:15], v[40:41], 0, s[10:11]
	global_load_lds_dwordx4 v[14:15], off
	v_lshl_add_u64 v[14:15], v[88:89], 0, s[10:11]
	s_mov_b32 m0, s34
	v_mfma_f32_16x16x32_bf16 v[68:71], v[22:25], v[68:71], 0
	global_load_lds_dwordx4 v[14:15], off
	v_lshl_add_u64 v[14:15], v[90:91], 0, s[10:11]
	s_mov_b32 m0, s35
	v_mfma_f32_16x16x32_bf16 v[22:25], v[22:25], v[80:83], 0
	global_load_lds_dwordx4 v[14:15], off
	v_lshl_add_u64 v[14:15], v[92:93], 0, s[10:11]
	s_mov_b32 m0, s36
	v_mfma_f32_16x16x32_bf16 v[64:67], v[26:29], v[72:75], v[68:71]
	global_load_lds_dwordx4 v[14:15], off
	s_waitcnt vmcnt(8)
	s_barrier
	ds_read_b128 v[14:17], v57 offset:50176
	v_mfma_f32_16x16x32_bf16 v[22:25], v[26:29], v[84:87], v[22:25]
	ds_read_b128 v[26:29], v47 offset:33792
	ds_read_b128 v[68:71], v47 offset:34816
	ds_read_b128 v[72:75], v57 offset:51200
	ds_read_b128 v[76:79], v57 offset:52224
	ds_read_b128 v[80:83], v57 offset:53248
	v_or_b32_e32 v40, s12, v48
	s_waitcnt lgkmcnt(0)
	v_mfma_f32_16x16x32_bf16 v[18:21], v[14:17], v[26:29], v[18:21]
	v_cmp_gt_i32_e32 vcc, s45, v40
	v_ashrrev_i32_e32 v41, 31, v40
	v_mfma_f32_16x16x32_bf16 v[6:9], v[76:79], v[26:29], v[6:9]
	ds_read_b128 v[26:29], v47 offset:35840
	ds_read_b128 v[84:87], v47 offset:36864
	s_waitcnt lgkmcnt(0)
	v_mfma_f32_16x16x32_bf16 v[10:13], v[14:17], v[26:29], v[10:13]
	v_mfma_f32_16x16x32_bf16 v[26:29], v[76:79], v[26:29], v[30:33]
	s_nop 2
	ds_read_b128 v[30:33], v47 offset:37888
	ds_read_b128 v[88:91], v47 offset:38912
	s_waitcnt lgkmcnt(0)
	v_mfma_f32_16x16x32_bf16 v[60:63], v[14:17], v[30:33], v[60:63]
	v_mfma_f32_16x16x32_bf16 v[30:33], v[76:79], v[30:33], v[64:67]
	s_nop 2
	ds_read_b128 v[64:67], v47 offset:39936
	ds_read_b128 v[92:95], v47 offset:40960
	s_waitcnt lgkmcnt(0)
	s_barrier
	s_waitcnt vmcnt(4)
	s_barrier
	s_waitcnt lgkmcnt(0)
	v_mfma_f32_16x16x32_bf16 v[2:5], v[14:17], v[64:67], v[2:5]
	v_mfma_f32_16x16x32_bf16 v[14:17], v[76:79], v[64:67], v[22:25]
	v_mfma_f32_16x16x32_bf16 v[22:25], v[80:83], v[84:87], v[26:29]
	v_mfma_f32_16x16x32_bf16 v[26:29], v[72:75], v[88:91], v[60:63]
	s_nop 2
	ds_read_b128 v[60:63], v58
	v_mfma_f32_16x16x32_bf16 v[18:21], v[72:75], v[68:71], v[18:21]
	v_mfma_f32_16x16x32_bf16 v[6:9], v[80:83], v[68:71], v[6:9]
	v_mfma_f32_16x16x32_bf16 v[10:13], v[72:75], v[84:87], v[10:13]
	v_mfma_f32_16x16x32_bf16 v[30:33], v[80:83], v[88:91], v[30:33]
	v_mfma_f32_16x16x32_bf16 v[2:5], v[72:75], v[92:95], v[2:5]
	ds_read_b128 v[64:67], v49
	ds_read_b128 v[68:71], v50
	ds_read_b128 v[72:75], v58 offset:1024
	v_mfma_f32_16x16x32_bf16 v[14:17], v[80:83], v[92:95], v[14:17]
	ds_read_b128 v[76:79], v58 offset:2048
	ds_read_b128 v[80:83], v58 offset:3072
	s_waitcnt lgkmcnt(0)
	v_mfma_f32_16x16x32_bf16 v[18:21], v[60:63], v[64:67], v[18:21]
	v_mfma_f32_16x16x32_bf16 v[6:9], v[76:79], v[64:67], v[6:9]
	ds_read_b128 v[64:67], v51
	ds_read_b128 v[84:87], v52
	s_waitcnt lgkmcnt(0)
	v_mfma_f32_16x16x32_bf16 v[10:13], v[60:63], v[64:67], v[10:13]
	v_mfma_f32_16x16x32_bf16 v[22:25], v[76:79], v[64:67], v[22:25]
	ds_read_b128 v[64:67], v53
	ds_read_b128 v[88:91], v54
	s_waitcnt lgkmcnt(0)
	v_mfma_f32_16x16x32_bf16 v[26:29], v[60:63], v[64:67], v[26:29]
	v_mfma_f32_16x16x32_bf16 v[30:33], v[76:79], v[64:67], v[30:33]
	ds_read_b128 v[64:67], v55
	ds_read_b128 v[92:95], v56
	s_waitcnt lgkmcnt(0)
	s_barrier
	s_waitcnt vmcnt(0)
	s_barrier
	s_waitcnt lgkmcnt(0)
	v_mfma_f32_16x16x32_bf16 v[2:5], v[60:63], v[64:67], v[2:5]
	ds_read_b128 v[60:63], v57 offset:17408
	v_mfma_f32_16x16x32_bf16 v[14:17], v[76:79], v[64:67], v[14:17]
	v_mfma_f32_16x16x32_bf16 v[18:21], v[72:75], v[68:71], v[18:21]
	v_mfma_f32_16x16x32_bf16 v[6:9], v[80:83], v[68:71], v[6:9]
	v_mfma_f32_16x16x32_bf16 v[10:13], v[72:75], v[84:87], v[10:13]
	v_mfma_f32_16x16x32_bf16 v[22:25], v[80:83], v[84:87], v[22:25]
	v_mfma_f32_16x16x32_bf16 v[26:29], v[72:75], v[88:91], v[26:29]
	v_mfma_f32_16x16x32_bf16 v[30:33], v[80:83], v[88:91], v[30:33]
	v_mfma_f32_16x16x32_bf16 v[2:5], v[72:75], v[92:95], v[2:5]
	ds_read_b128 v[64:67], v47 offset:1024
	ds_read_b128 v[68:71], v47 offset:2048
	ds_read_b128 v[72:75], v57 offset:18432
	v_mfma_f32_16x16x32_bf16 v[14:17], v[80:83], v[92:95], v[14:17]
	ds_read_b128 v[76:79], v57 offset:19456
	ds_read_b128 v[80:83], v57 offset:20480
	s_waitcnt lgkmcnt(0)
	v_mfma_f32_16x16x32_bf16 v[18:21], v[60:63], v[64:67], v[18:21]
	v_mfma_f32_16x16x32_bf16 v[6:9], v[76:79], v[64:67], v[6:9]
	ds_read_b128 v[64:67], v47 offset:3072
	ds_read_b128 v[84:87], v47 offset:4096
	s_waitcnt lgkmcnt(0)
	v_mfma_f32_16x16x32_bf16 v[10:13], v[60:63], v[64:67], v[10:13]
	v_mfma_f32_16x16x32_bf16 v[64:67], v[76:79], v[64:67], v[22:25]
	s_nop 2
	ds_read_b128 v[22:25], v47 offset:5120
	ds_read_b128 v[88:91], v47 offset:6144
	s_waitcnt lgkmcnt(0)
	v_mfma_f32_16x16x32_bf16 v[92:95], v[60:63], v[22:25], v[26:29]
	v_mfma_f32_16x16x32_bf16 v[96:99], v[76:79], v[22:25], v[30:33]
	ds_read_b128 v[22:25], v47 offset:7168
	ds_read_b128 v[100:103], v47 offset:8192
	s_waitcnt lgkmcnt(0)
	s_barrier
	s_waitcnt lgkmcnt(0)
	v_mfma_f32_16x16x32_bf16 v[2:5], v[60:63], v[22:25], v[2:5]
	v_mfma_f32_16x16x32_bf16 v[60:63], v[76:79], v[22:25], v[14:17]
	v_mfma_f32_16x16x32_bf16 v[30:33], v[72:75], v[68:71], v[18:21]
	v_mfma_f32_16x16x32_bf16 v[26:29], v[80:83], v[68:71], v[6:9]
	v_mfma_f32_16x16x32_bf16 v[22:25], v[72:75], v[84:87], v[10:13]
	v_mfma_f32_16x16x32_bf16 v[18:21], v[80:83], v[84:87], v[64:67]
	v_mfma_f32_16x16x32_bf16 v[14:17], v[72:75], v[88:91], v[92:95]
	v_mfma_f32_16x16x32_bf16 v[10:13], v[80:83], v[88:91], v[96:99]
	v_mfma_f32_16x16x32_bf16 v[6:9], v[72:75], v[100:103], v[2:5]
	v_mfma_f32_16x16x32_bf16 v[2:5], v[80:83], v[100:103], v[60:63]
	s_and_saveexec_b64 s[2:3], vcc
	s_cbranch_execz .LBB0_717
	s_nop 0
	v_mov_b64_e32 v[60:61], s[4:5]
	v_mad_i64_i32 v[60:61], s[12:13], v59, s46, v[60:61]
	v_lshl_add_u64 v[60:61], v[40:41], 2, v[60:61]
	global_store_dwordx4 v[60:61], v[30:33], off sc1

.LBB0_724:
	v_mov_b64_e32 v[30:31], s[4:5]
	v_mad_i64_i32 v[30:31], s[48:49], v59, s46, v[30:31]
	v_lshl_add_u64 v[30:31], v[40:41], 2, v[30:31]
	global_store_dwordx4 v[30:31], v[26:29], off offset:64 sc1
	s_or_b64 exec, exec, s[12:13]
	s_nop 0
	v_add_u32_e32 v26, 16, v59
	s_and_saveexec_b64 s[12:13], vcc
	s_cbranch_execz .LBB0_719
.LBB0_725:
	v_mov_b64_e32 v[28:29], s[4:5]
	v_mad_i64_i32 v[28:29], s[48:49], v26, s46, v[28:29]
	v_lshl_add_u64 v[28:29], v[40:41], 2, v[28:29]
	global_store_dwordx4 v[28:29], v[22:25], off sc1
	s_or_b64 exec, exec, s[12:13]
	s_and_saveexec_b64 s[12:13], s[2:3]
	s_cbranch_execz .LBB0_720
.LBB0_726:
	v_mov_b64_e32 v[22:23], s[4:5]
	v_mad_i64_i32 v[22:23], s[48:49], v26, s46, v[22:23]
	v_lshl_add_u64 v[22:23], v[40:41], 2, v[22:23]
	global_store_dwordx4 v[22:23], v[18:21], off offset:64 sc1
	s_or_b64 exec, exec, s[12:13]
	s_nop 0
	v_add_u32_e32 v18, 32, v59
	s_and_saveexec_b64 s[12:13], vcc
	s_cbranch_execz .LBB0_721
.LBB0_727:
	v_mov_b64_e32 v[20:21], s[4:5]
	v_mad_i64_i32 v[20:21], s[48:49], v18, s46, v[20:21]
	v_lshl_add_u64 v[20:21], v[40:41], 2, v[20:21]
	global_store_dwordx4 v[20:21], v[14:17], off sc1
	s_or_b64 exec, exec, s[12:13]
	s_and_saveexec_b64 s[12:13], s[2:3]
	s_cbranch_execz .LBB0_722
.LBB0_728:
	v_mov_b64_e32 v[14:15], s[4:5]
	v_mad_i64_i32 v[14:15], s[48:49], v18, s46, v[14:15]
	v_lshl_add_u64 v[14:15], v[40:41], 2, v[14:15]
	global_store_dwordx4 v[14:15], v[10:13], off offset:64 sc1
	s_or_b64 exec, exec, s[12:13]
	s_nop 0
	v_add_u32_e32 v10, 48, v59
	s_and_saveexec_b64 s[12:13], vcc
	s_cbranch_execz .LBB0_723
.LBB0_729:
	v_mov_b64_e32 v[12:13], s[4:5]
	v_mad_i64_i32 v[12:13], s[48:49], v10, s46, v[12:13]
	v_lshl_add_u64 v[12:13], v[40:41], 2, v[12:13]
	global_store_dwordx4 v[12:13], v[6:9], off sc1
	s_or_b64 exec, exec, s[12:13]
	s_and_saveexec_b64 s[12:13], s[2:3]
	s_cbranch_execz .LBB0_714
.LBB0_730:
	v_mov_b64_e32 v[6:7], s[4:5]
	v_mad_i64_i32 v[6:7], s[2:3], v10, s46, v[6:7]
	v_lshl_add_u64 v[6:7], v[40:41], 2, v[6:7]
	global_store_dwordx4 v[6:7], v[2:5], off offset:64 sc1
	s_branch .LBB0_714

.LBB0_734:
	s_mul_hi_i32 s2, s10, 0x92492493
	s_add_i32 s2, s2, s10
	s_lshr_b32 s3, s2, 31
	s_ashr_i32 s2, s2, 5
	s_add_i32 s8, s2, s3
	s_mul_i32 s2, s8, 0xffffe400
	s_add_i32 s2, s18, s2
	s_ashr_i32 s3, s2, 31
	s_lshl_b32 s8, s8, 7
	s_ashr_i32 s9, s8, 31
	s_lshl_b64 s[34:35], s[2:3], 8
	s_add_u32 s34, s11, s34
	s_addc_u32 s35, s12, s35
	s_lshl_b64 s[36:37], s[8:9], 8
	s_add_u32 s36, s13, s36
	v_lshl_add_u64 v[2:3], s[34:35], 0, v[34:35]
	s_mov_b32 m0, s21
	s_addc_u32 s37, s22, s37
	v_lshl_add_u64 v[2:3], v[2:3], 0, v[36:37]
	v_lshl_add_u64 v[4:5], s[34:35], 0, v[38:39]
	global_load_lds_dwordx4 v[2:3], off
	v_lshl_add_u64 v[4:5], v[4:5], 0, v[36:37]
	s_mov_b32 m0, s23
	v_lshl_add_u64 v[6:7], s[36:37], 0, v[34:35]
	global_load_lds_dwordx4 v[4:5], off
	v_lshl_add_u64 v[6:7], v[6:7], 0, v[36:37]
	s_mov_b32 m0, s24
	v_lshl_add_u64 v[8:9], s[36:37], 0, v[38:39]
	global_load_lds_dwordx4 v[6:7], off
	v_lshl_add_u64 v[8:9], v[8:9], 0, v[36:37]
	s_mov_b32 m0, s25
	v_lshl_add_u64 v[2:3], v[2:3], 0, s[6:7]
	global_load_lds_dwordx4 v[8:9], off
	s_mov_b32 m0, s26
	s_nop 0
	global_load_lds_dwordx4 v[2:3], off
	v_lshl_add_u64 v[2:3], v[4:5], 0, s[6:7]
	s_mov_b32 m0, s27
	s_nop 0
	global_load_lds_dwordx4 v[2:3], off
	v_lshl_add_u64 v[2:3], v[6:7], 0, s[6:7]
	s_mov_b32 m0, s28
	s_nop 0
	global_load_lds_dwordx4 v[2:3], off
	v_lshl_add_u64 v[2:3], v[8:9], 0, s[6:7]
	s_mov_b32 m0, s29
	s_nop 0
	global_load_lds_dwordx4 v[2:3], off
	s_waitcnt vmcnt(4)
	s_barrier
	ds_read_b128 v[2:5], v49 offset:17408
	ds_read_b128 v[6:9], v48 offset:1024
	ds_read_b128 v[10:13], v48 offset:2048
	ds_read_b128 v[14:17], v49 offset:18432
	ds_read_b128 v[22:25], v49 offset:19456
	ds_read_b128 v[26:29], v49 offset:20480
	ds_read_b128 v[30:33], v48 offset:3072
	ds_read_b128 v[40:43], v48 offset:4096
	ds_read_b128 v[54:57], v48 offset:5120
	ds_read_b128 v[58:61], v48 offset:6144
	ds_read_b128 v[66:69], v48 offset:7168
	ds_read_b128 v[70:73], v48 offset:8192
	s_waitcnt lgkmcnt(0)
	v_mfma_f32_16x16x32_bf16 v[18:21], v[2:5], v[6:9], 0
	s_waitcnt lgkmcnt(0)
	s_barrier
	v_mfma_f32_16x16x32_bf16 v[6:9], v[22:25], v[6:9], 0
	s_waitcnt vmcnt(0)
	s_barrier
	v_mfma_f32_16x16x32_bf16 v[50:53], v[2:5], v[30:33], 0
	v_mfma_f32_16x16x32_bf16 v[30:33], v[22:25], v[30:33], 0
	v_mfma_f32_16x16x32_bf16 v[62:65], v[2:5], v[54:57], 0
	v_mfma_f32_16x16x32_bf16 v[2:5], v[2:5], v[66:69], 0
	v_mfma_f32_16x16x32_bf16 v[18:21], v[14:17], v[10:13], v[18:21]
	v_mfma_f32_16x16x32_bf16 v[6:9], v[26:29], v[10:13], v[6:9]
	v_mfma_f32_16x16x32_bf16 v[10:13], v[14:17], v[40:43], v[50:53]
	v_mfma_f32_16x16x32_bf16 v[30:33], v[26:29], v[40:43], v[30:33]
	v_mfma_f32_16x16x32_bf16 v[40:43], v[14:17], v[58:61], v[62:65]
	v_mfma_f32_16x16x32_bf16 v[2:5], v[14:17], v[70:73], v[2:5]
	ds_read_b128 v[14:17], v49 offset:50176
	v_mfma_f32_16x16x32_bf16 v[54:57], v[22:25], v[54:57], 0
	v_mfma_f32_16x16x32_bf16 v[22:25], v[22:25], v[66:69], 0
	v_mfma_f32_16x16x32_bf16 v[50:53], v[26:29], v[58:61], v[54:57]
	v_mfma_f32_16x16x32_bf16 v[22:25], v[26:29], v[70:73], v[22:25]
	ds_read_b128 v[26:29], v48 offset:33792
	s_nop 3
	ds_read_b128 v[54:57], v48 offset:34816
	ds_read_b128 v[58:61], v49 offset:51200
	ds_read_b128 v[62:65], v49 offset:52224
	ds_read_b128 v[66:69], v49 offset:53248
	s_waitcnt lgkmcnt(0)
	v_mfma_f32_16x16x32_bf16 v[18:21], v[14:17], v[26:29], v[18:21]
	v_mfma_f32_16x16x32_bf16 v[6:9], v[62:65], v[26:29], v[6:9]
	ds_read_b128 v[26:29], v48 offset:35840
	ds_read_b128 v[70:73], v48 offset:36864
	s_waitcnt lgkmcnt(0)
	v_mfma_f32_16x16x32_bf16 v[10:13], v[14:17], v[26:29], v[10:13]
	v_mfma_f32_16x16x32_bf16 v[74:77], v[62:65], v[26:29], v[30:33]
	ds_read_b128 v[26:29], v48 offset:37888
	ds_read_b128 v[78:81], v48 offset:38912
	s_waitcnt lgkmcnt(0)
	v_mfma_f32_16x16x32_bf16 v[40:43], v[14:17], v[26:29], v[40:43]
	v_mfma_f32_16x16x32_bf16 v[50:53], v[62:65], v[26:29], v[50:53]
	ds_read_b128 v[26:29], v48 offset:39936
	ds_read_b128 v[82:85], v48 offset:40960
	s_waitcnt lgkmcnt(0)
	s_barrier
	s_waitcnt lgkmcnt(0)
	v_mfma_f32_16x16x32_bf16 v[2:5], v[14:17], v[26:29], v[2:5]
	v_mfma_f32_16x16x32_bf16 v[62:65], v[62:65], v[26:29], v[22:25]
	v_mfma_f32_16x16x32_bf16 v[14:17], v[58:61], v[78:81], v[40:43]
	s_nop 2
	v_add_u32_e32 v42, s2, v46
	v_ashrrev_i32_e32 v43, 31, v42
	v_mfma_f32_16x16x32_bf16 v[26:29], v[66:69], v[54:57], v[6:9]
	v_or_b32_e32 v40, s8, v47
	v_cmp_gt_i32_e32 vcc, s20, v40
	v_ashrrev_i32_e32 v41, 31, v40
	v_mfma_f32_16x16x32_bf16 v[6:9], v[58:61], v[82:85], v[2:5]
	s_nop 2
	v_lshlrev_b64 v[2:3], 12, v[42:43]
	v_mfma_f32_16x16x32_bf16 v[30:33], v[58:61], v[54:57], v[18:21]
	v_lshl_add_u64 v[44:45], s[4:5], 0, v[2:3]
	v_mfma_f32_16x16x32_bf16 v[22:25], v[58:61], v[70:73], v[10:13]
	v_mfma_f32_16x16x32_bf16 v[18:21], v[66:69], v[70:73], v[74:77]
	v_mfma_f32_16x16x32_bf16 v[10:13], v[66:69], v[78:81], v[50:53]
	v_mfma_f32_16x16x32_bf16 v[2:5], v[66:69], v[82:85], v[62:65]
	s_and_saveexec_b64 s[2:3], vcc
	s_cbranch_execz .LBB0_736
	v_lshl_add_u64 v[50:51], v[40:41], 2, v[44:45]
	global_store_dwordx4 v[50:51], v[30:33], off sc1
.LBB0_736:
	s_or_b64 exec, exec, s[2:3]
	s_nop 0
	v_or_b32_e32 v30, 16, v40
	v_cmp_gt_i32_e64 s[2:3], s20, v30
	s_and_saveexec_b64 s[8:9], s[2:3]
	s_cbranch_execz .LBB0_738
	v_lshl_add_u64 v[30:31], v[40:41], 2, v[44:45]
	global_store_dwordx4 v[30:31], v[26:29], off offset:64 sc1
.LBB0_738:
	s_or_b64 exec, exec, s[8:9]
	s_nop 0
	v_add_u32_e32 v26, 16, v42
	v_ashrrev_i32_e32 v27, 31, v26
	v_lshlrev_b64 v[26:27], 12, v[26:27]
	v_lshl_add_u64 v[26:27], s[4:5], 0, v[26:27]
	s_and_saveexec_b64 s[8:9], vcc
	s_cbranch_execz .LBB0_740
	v_lshl_add_u64 v[28:29], v[40:41], 2, v[26:27]
	global_store_dwordx4 v[28:29], v[22:25], off sc1
.LBB0_740:
	s_or_b64 exec, exec, s[8:9]
	s_and_saveexec_b64 s[8:9], s[2:3]
	s_cbranch_execz .LBB0_742
	v_lshl_add_u64 v[22:23], v[40:41], 2, v[26:27]
	global_store_dwordx4 v[22:23], v[18:21], off offset:64 sc1
.LBB0_742:
	s_or_b64 exec, exec, s[8:9]
	s_nop 0
	v_add_u32_e32 v18, 32, v42
	v_ashrrev_i32_e32 v19, 31, v18
	v_lshlrev_b64 v[18:19], 12, v[18:19]
	v_lshl_add_u64 v[18:19], s[4:5], 0, v[18:19]
	s_and_saveexec_b64 s[8:9], vcc
	s_cbranch_execz .LBB0_744
	v_lshl_add_u64 v[20:21], v[40:41], 2, v[18:19]
	global_store_dwordx4 v[20:21], v[14:17], off sc1
.LBB0_744:
	s_or_b64 exec, exec, s[8:9]
	s_and_saveexec_b64 s[8:9], s[2:3]
	s_cbranch_execz .LBB0_746
	v_lshl_add_u64 v[14:15], v[40:41], 2, v[18:19]
	global_store_dwordx4 v[14:15], v[10:13], off offset:64 sc1
.LBB0_746:
	s_or_b64 exec, exec, s[8:9]
	s_nop 0
	v_add_u32_e32 v10, 48, v42
	v_ashrrev_i32_e32 v11, 31, v10
	v_lshlrev_b64 v[10:11], 12, v[10:11]
	v_lshl_add_u64 v[10:11], s[4:5], 0, v[10:11]
	s_and_saveexec_b64 s[8:9], vcc
	s_cbranch_execz .LBB0_748
	v_lshl_add_u64 v[12:13], v[40:41], 2, v[10:11]
	global_store_dwordx4 v[12:13], v[6:9], off sc1
.LBB0_748:
	s_or_b64 exec, exec, s[8:9]
	s_and_saveexec_b64 s[8:9], s[2:3]
	s_cbranch_execz .LBB0_733
	v_lshl_add_u64 v[6:7], v[40:41], 2, v[10:11]
	global_store_dwordx4 v[6:7], v[2:5], off offset:64 sc1
	s_branch .LBB0_733

.LBB0_793:
	v_mov_b32_e32 v88, v80
	v_mov_b32_e32 v89, v80
	v_pk_fma_f32 v[94:95], v[88:89], v[72:73], v[48:49]
	v_add_co_u32_e32 v88, vcc, 0x100000, v78
	v_pk_fma_f32 v[92:93], v[80:81], v[70:71], v[46:47]
	s_nop 0
	v_addc_co_u32_e32 v89, vcc, 0, v79, vcc
	global_store_dwordx4 v[88:89], v[70:73], off sc1
	s_nop 1
	v_mov_b64_e32 v[70:71], v[92:93]
	v_mov_b64_e32 v[72:73], v[94:95]
.LBB0_794:
	v_mov_b32_e32 v88, v80
	v_mov_b32_e32 v89, v80
	global_store_dwordx4 v[82:83], v[70:73], off sc1
	s_mov_b64 s[16:17], 0
	s_nop 0
	v_pk_fma_f32 v[72:73], v[88:89], v[72:73], v[52:53]
	v_pk_fma_f32 v[70:71], v[80:81], v[70:71], v[50:51]
	global_store_dwordx4 v[86:87], v[70:73], off sc1
	s_nop 1
	v_pk_fma_f32 v[72:73], v[88:89], v[72:73], v[56:57]
	v_pk_fma_f32 v[70:71], v[80:81], v[70:71], v[54:55]
	global_store_dwordx4 v[84:85], v[70:73], off sc1
	s_nop 1
	v_pk_fma_f32 v[72:73], v[88:89], v[72:73], v[60:61]
	v_pk_fma_f32 v[70:71], v[80:81], v[70:71], v[58:59]
	global_store_dwordx4 v[78:79], v[70:73], off sc1
	s_nop 1
	v_pk_fma_f32 v[72:73], v[88:89], v[72:73], v[64:65]
	v_pk_fma_f32 v[70:71], v[80:81], v[70:71], v[62:63]
.LBB0_795:
	s_and_b64 vcc, exec, s[16:17]
	s_cbranch_vccz .LBB0_809
	v_mov_b32_e32 v88, v80
	v_mov_b32_e32 v89, v80
	v_pk_fma_f32 v[64:65], v[88:89], v[68:69], v[64:65]
	v_pk_fma_f32 v[62:63], v[80:81], v[66:67], v[62:63]
	v_pk_fma_f32 v[60:61], v[88:89], v[64:65], v[60:61]
	v_pk_fma_f32 v[58:59], v[80:81], v[62:63], v[58:59]
	v_pk_fma_f32 v[56:57], v[88:89], v[60:61], v[56:57]
	v_pk_fma_f32 v[54:55], v[80:81], v[58:59], v[54:55]
	v_pk_fma_f32 v[72:73], v[88:89], v[56:57], v[52:53]
	s_and_b64 vcc, exec, s[2:3]
	v_pk_fma_f32 v[70:71], v[80:81], v[54:55], v[50:51]
	global_store_dwordx4 v[78:79], v[66:69], off sc1
	global_store_dwordx4 v[84:85], v[62:65], off sc1
	global_store_dwordx4 v[86:87], v[58:61], off sc1
	global_store_dwordx4 v[82:83], v[54:57], off sc1
	s_cbranch_vccz .LBB0_822
	s_and_b64 vcc, exec, s[2:3]
	s_cbranch_vccz .LBB0_823

.LBB0_808:
	v_mov_b32_e32 v50, v80
	v_mov_b32_e32 v51, v80
	v_add_co_u32_e32 v54, vcc, 0x3c0000, v78
	v_pk_fma_f32 v[52:53], v[50:51], v[72:73], v[4:5]
	s_nop 0
	v_addc_co_u32_e32 v55, vcc, 0, v79, vcc
	v_pk_fma_f32 v[50:51], v[80:81], v[70:71], v[2:3]
	global_store_dwordx4 v[54:55], v[70:73], off sc1
	s_nop 1
	v_mov_b64_e32 v[72:73], v[52:53]
	v_mov_b64_e32 v[70:71], v[50:51]
.LBB0_809:
	s_andn2_b64 vcc, exec, s[12:13]
	s_cbranch_vccnz .LBB0_752
	ds_read_b64 v[50:51], v75 offset:408
	s_lshl_b32 s2, s27, 3
	s_or_b32 s2, s28, s2
	s_or_b32 s2, s2, s26
	s_ashr_i32 s3, s2, 31
	s_waitcnt lgkmcnt(0)
	v_readfirstlane_b32 s4, v50
	s_lshl_b64 s[2:3], s[2:3], 15
	v_readfirstlane_b32 s12, v51
	s_add_u32 s2, s4, s2
	s_addc_u32 s3, s12, s3
	v_lshl_add_u64 v[50:51], s[2:3], 0, v[74:75]
	v_add_co_u32_e32 v50, vcc, 0x1a80000, v50
	s_nop 1
	v_addc_co_u32_e32 v51, vcc, 0, v51, vcc
	global_store_dwordx4 v[50:51], v[70:73], off sc1
	s_branch .LBB0_752
.LBB0_811:
	v_mov_b32_e32 v70, v80
	v_mov_b32_e32 v71, v80
	v_add_co_u32_e32 v88, vcc, 0x3c0000, v78
	v_pk_fma_f32 v[72:73], v[70:71], v[68:69], v[4:5]
	v_pk_fma_f32 v[70:71], v[80:81], v[66:67], v[2:3]
	v_addc_co_u32_e32 v89, vcc, 0, v79, vcc
	global_store_dwordx4 v[88:89], v[66:69], off sc1
	s_and_b64 vcc, exec, s[2:3]
	s_cbranch_vccnz .LBB0_783
.LBB0_812:
	v_mov_b32_e32 v88, v80
	v_mov_b32_e32 v89, v80
	v_pk_fma_f32 v[94:95], v[88:89], v[72:73], v[8:9]
	v_add_co_u32_e32 v88, vcc, 0x380000, v78
	v_pk_fma_f32 v[92:93], v[80:81], v[70:71], v[6:7]
	s_nop 0
	v_addc_co_u32_e32 v89, vcc, 0, v79, vcc
	global_store_dwordx4 v[88:89], v[70:73], off sc1
	s_nop 1
	v_mov_b64_e32 v[70:71], v[92:93]
	v_mov_b64_e32 v[72:73], v[94:95]
	s_and_b64 vcc, exec, s[2:3]
	s_cbranch_vccnz .LBB0_784
.LBB0_813:
	v_mov_b32_e32 v88, v80
	v_mov_b32_e32 v89, v80
	v_pk_fma_f32 v[94:95], v[88:89], v[72:73], v[12:13]
	v_add_co_u32_e32 v88, vcc, 0x340000, v78
	v_pk_fma_f32 v[92:93], v[80:81], v[70:71], v[10:11]
	s_nop 0
	v_addc_co_u32_e32 v89, vcc, 0, v79, vcc
	global_store_dwordx4 v[88:89], v[70:73], off sc1
	s_nop 1
	v_mov_b64_e32 v[70:71], v[92:93]
	v_mov_b64_e32 v[72:73], v[94:95]
	s_and_b64 vcc, exec, s[2:3]
	s_cbranch_vccnz .LBB0_785
.LBB0_814:
	v_mov_b32_e32 v88, v80
	v_mov_b32_e32 v89, v80
	v_pk_fma_f32 v[94:95], v[88:89], v[72:73], v[16:17]
	v_add_co_u32_e32 v88, vcc, 0x300000, v78
	v_pk_fma_f32 v[92:93], v[80:81], v[70:71], v[14:15]
	s_nop 0
	v_addc_co_u32_e32 v89, vcc, 0, v79, vcc
	global_store_dwordx4 v[88:89], v[70:73], off sc1
	s_nop 1
	v_mov_b64_e32 v[70:71], v[92:93]
	v_mov_b64_e32 v[72:73], v[94:95]
	s_and_b64 vcc, exec, s[2:3]
	s_cbranch_vccnz .LBB0_786
.LBB0_815:
	v_mov_b32_e32 v88, v80
	v_mov_b32_e32 v89, v80
	v_pk_fma_f32 v[94:95], v[88:89], v[72:73], v[20:21]
	v_add_co_u32_e32 v88, vcc, 0x2c0000, v78
	v_pk_fma_f32 v[92:93], v[80:81], v[70:71], v[18:19]
	s_nop 0
	v_addc_co_u32_e32 v89, vcc, 0, v79, vcc
	global_store_dwordx4 v[88:89], v[70:73], off sc1
	s_nop 1
	v_mov_b64_e32 v[70:71], v[92:93]
	v_mov_b64_e32 v[72:73], v[94:95]
	s_and_b64 vcc, exec, s[2:3]
	s_cbranch_vccnz .LBB0_787
.LBB0_816:
	v_mov_b32_e32 v88, v80
	v_mov_b32_e32 v89, v80
	v_pk_fma_f32 v[94:95], v[88:89], v[72:73], v[24:25]
	v_add_co_u32_e32 v88, vcc, 0x280000, v78
	v_pk_fma_f32 v[92:93], v[80:81], v[70:71], v[22:23]
	s_nop 0
	v_addc_co_u32_e32 v89, vcc, 0, v79, vcc
	global_store_dwordx4 v[88:89], v[70:73], off sc1
	s_nop 1
	v_mov_b64_e32 v[70:71], v[92:93]
	v_mov_b64_e32 v[72:73], v[94:95]
	s_and_b64 vcc, exec, s[2:3]
	s_cbranch_vccnz .LBB0_788
.LBB0_817:
	v_mov_b32_e32 v88, v80
	v_mov_b32_e32 v89, v80
	v_pk_fma_f32 v[94:95], v[88:89], v[72:73], v[28:29]
	v_add_co_u32_e32 v88, vcc, 0x240000, v78
	v_pk_fma_f32 v[92:93], v[80:81], v[70:71], v[26:27]
	s_nop 0
	v_addc_co_u32_e32 v89, vcc, 0, v79, vcc
	global_store_dwordx4 v[88:89], v[70:73], off sc1
	s_nop 1
	v_mov_b64_e32 v[70:71], v[92:93]
	v_mov_b64_e32 v[72:73], v[94:95]
	s_and_b64 vcc, exec, s[2:3]
	s_cbranch_vccnz .LBB0_789
.LBB0_818:
	v_mov_b32_e32 v88, v80
	v_mov_b32_e32 v89, v80
	v_pk_fma_f32 v[94:95], v[88:89], v[72:73], v[32:33]
	v_add_co_u32_e32 v88, vcc, 0x200000, v78
	v_pk_fma_f32 v[92:93], v[80:81], v[70:71], v[30:31]
	s_nop 0
	v_addc_co_u32_e32 v89, vcc, 0, v79, vcc
	global_store_dwordx4 v[88:89], v[70:73], off sc1
	s_nop 1
	v_mov_b64_e32 v[70:71], v[92:93]
	v_mov_b64_e32 v[72:73], v[94:95]
	s_and_b64 vcc, exec, s[2:3]
	s_cbranch_vccnz .LBB0_790
.LBB0_819:
	v_mov_b32_e32 v88, v80
	v_mov_b32_e32 v89, v80
	v_pk_fma_f32 v[94:95], v[88:89], v[72:73], v[36:37]
	v_add_co_u32_e32 v88, vcc, 0x1c0000, v78
	v_pk_fma_f32 v[92:93], v[80:81], v[70:71], v[34:35]
	s_nop 0
	v_addc_co_u32_e32 v89, vcc, 0, v79, vcc
	global_store_dwordx4 v[88:89], v[70:73], off sc1
	s_nop 1
	v_mov_b64_e32 v[70:71], v[92:93]
	v_mov_b64_e32 v[72:73], v[94:95]
	s_and_b64 vcc, exec, s[2:3]
	s_cbranch_vccnz .LBB0_791
.LBB0_820:
	v_mov_b32_e32 v88, v80
	v_mov_b32_e32 v89, v80
	v_pk_fma_f32 v[94:95], v[88:89], v[72:73], v[40:41]
	v_add_co_u32_e32 v88, vcc, 0x180000, v78
	v_pk_fma_f32 v[92:93], v[80:81], v[70:71], v[38:39]
	s_nop 0
	v_addc_co_u32_e32 v89, vcc, 0, v79, vcc
	global_store_dwordx4 v[88:89], v[70:73], off sc1
	s_nop 1
	v_mov_b64_e32 v[70:71], v[92:93]
	v_mov_b64_e32 v[72:73], v[94:95]
	s_and_b64 vcc, exec, s[2:3]
	s_cbranch_vccnz .LBB0_792
.LBB0_821:
	v_mov_b32_e32 v88, v80
	v_mov_b32_e32 v89, v80
	v_pk_fma_f32 v[94:95], v[88:89], v[72:73], v[44:45]
	v_add_co_u32_e32 v88, vcc, 0x140000, v78
	v_pk_fma_f32 v[92:93], v[80:81], v[70:71], v[42:43]
	s_nop 0
	v_addc_co_u32_e32 v89, vcc, 0, v79, vcc
	global_store_dwordx4 v[88:89], v[70:73], off sc1
	s_nop 1
	v_mov_b64_e32 v[70:71], v[92:93]
	v_mov_b64_e32 v[72:73], v[94:95]
	s_and_b64 vcc, exec, s[2:3]
	s_cbranch_vccz .LBB0_793
	s_branch .LBB0_794
.LBB0_822:
	s_nop 0
	v_add_co_u32_e32 v54, vcc, 0x100000, v78
	v_pk_fma_f32 v[52:53], v[88:89], v[72:73], v[48:49]
	s_nop 0
	v_addc_co_u32_e32 v55, vcc, 0, v79, vcc
	v_pk_fma_f32 v[50:51], v[80:81], v[70:71], v[46:47]
	global_store_dwordx4 v[54:55], v[70:73], off sc1
	s_nop 1
	v_mov_b64_e32 v[72:73], v[52:53]
	v_mov_b64_e32 v[70:71], v[50:51]
	s_and_b64 vcc, exec, s[2:3]
	s_cbranch_vccnz .LBB0_798
.LBB0_823:
	v_mov_b32_e32 v50, v80
	v_mov_b32_e32 v51, v80
	v_add_co_u32_e32 v54, vcc, 0x140000, v78
	v_pk_fma_f32 v[52:53], v[50:51], v[72:73], v[44:45]
	s_nop 0
	v_addc_co_u32_e32 v55, vcc, 0, v79, vcc
	v_pk_fma_f32 v[50:51], v[80:81], v[70:71], v[42:43]
	global_store_dwordx4 v[54:55], v[70:73], off sc1
	s_nop 1
	v_mov_b64_e32 v[72:73], v[52:53]
	v_mov_b64_e32 v[70:71], v[50:51]
	s_and_b64 vcc, exec, s[2:3]
	s_cbranch_vccnz .LBB0_799
.LBB0_824:
	v_mov_b32_e32 v50, v80
	v_mov_b32_e32 v51, v80
	v_add_co_u32_e32 v54, vcc, 0x180000, v78
	v_pk_fma_f32 v[52:53], v[50:51], v[72:73], v[40:41]
	s_nop 0
	v_addc_co_u32_e32 v55, vcc, 0, v79, vcc
	v_pk_fma_f32 v[50:51], v[80:81], v[70:71], v[38:39]
	global_store_dwordx4 v[54:55], v[70:73], off sc1
	s_nop 1
	v_mov_b64_e32 v[72:73], v[52:53]
	v_mov_b64_e32 v[70:71], v[50:51]
	s_and_b64 vcc, exec, s[2:3]
	s_cbranch_vccnz .LBB0_800
.LBB0_825:
	v_mov_b32_e32 v50, v80
	v_mov_b32_e32 v51, v80
	v_add_co_u32_e32 v54, vcc, 0x1c0000, v78
	v_pk_fma_f32 v[52:53], v[50:51], v[72:73], v[36:37]
	s_nop 0
	v_addc_co_u32_e32 v55, vcc, 0, v79, vcc
	v_pk_fma_f32 v[50:51], v[80:81], v[70:71], v[34:35]
	global_store_dwordx4 v[54:55], v[70:73], off sc1
	s_nop 1
	v_mov_b64_e32 v[72:73], v[52:53]
	v_mov_b64_e32 v[70:71], v[50:51]
	s_and_b64 vcc, exec, s[2:3]
	s_cbranch_vccnz .LBB0_801
.LBB0_826:
	v_mov_b32_e32 v50, v80
	v_mov_b32_e32 v51, v80
	v_add_co_u32_e32 v54, vcc, 0x200000, v78
	v_pk_fma_f32 v[52:53], v[50:51], v[72:73], v[32:33]
	s_nop 0
	v_addc_co_u32_e32 v55, vcc, 0, v79, vcc
	v_pk_fma_f32 v[50:51], v[80:81], v[70:71], v[30:31]
	global_store_dwordx4 v[54:55], v[70:73], off sc1
	s_nop 1
	v_mov_b64_e32 v[72:73], v[52:53]
	v_mov_b64_e32 v[70:71], v[50:51]
	s_and_b64 vcc, exec, s[2:3]
	s_cbranch_vccnz .LBB0_802
.LBB0_827:
	v_mov_b32_e32 v50, v80
	v_mov_b32_e32 v51, v80
	v_add_co_u32_e32 v54, vcc, 0x240000, v78
	v_pk_fma_f32 v[52:53], v[50:51], v[72:73], v[28:29]
	s_nop 0
	v_addc_co_u32_e32 v55, vcc, 0, v79, vcc
	v_pk_fma_f32 v[50:51], v[80:81], v[70:71], v[26:27]
	global_store_dwordx4 v[54:55], v[70:73], off sc1
	s_nop 1
	v_mov_b64_e32 v[72:73], v[52:53]
	v_mov_b64_e32 v[70:71], v[50:51]
	s_and_b64 vcc, exec, s[2:3]
	s_cbranch_vccnz .LBB0_803
.LBB0_828:
	v_mov_b32_e32 v50, v80
	v_mov_b32_e32 v51, v80
	v_add_co_u32_e32 v54, vcc, 0x280000, v78
	v_pk_fma_f32 v[52:53], v[50:51], v[72:73], v[24:25]
	s_nop 0
	v_addc_co_u32_e32 v55, vcc, 0, v79, vcc
	v_pk_fma_f32 v[50:51], v[80:81], v[70:71], v[22:23]
	global_store_dwordx4 v[54:55], v[70:73], off sc1
	s_nop 1
	v_mov_b64_e32 v[72:73], v[52:53]
	v_mov_b64_e32 v[70:71], v[50:51]
	s_and_b64 vcc, exec, s[2:3]
	s_cbranch_vccnz .LBB0_804
.LBB0_829:
	v_mov_b32_e32 v50, v80
	v_mov_b32_e32 v51, v80
	v_add_co_u32_e32 v54, vcc, 0x2c0000, v78
	v_pk_fma_f32 v[52:53], v[50:51], v[72:73], v[20:21]
	s_nop 0
	v_addc_co_u32_e32 v55, vcc, 0, v79, vcc
	v_pk_fma_f32 v[50:51], v[80:81], v[70:71], v[18:19]
	global_store_dwordx4 v[54:55], v[70:73], off sc1
	s_nop 1
	v_mov_b64_e32 v[72:73], v[52:53]
	v_mov_b64_e32 v[70:71], v[50:51]
	s_and_b64 vcc, exec, s[2:3]
	s_cbranch_vccnz .LBB0_805
.LBB0_830:
	v_mov_b32_e32 v50, v80
	v_mov_b32_e32 v51, v80
	v_add_co_u32_e32 v54, vcc, 0x300000, v78
	v_pk_fma_f32 v[52:53], v[50:51], v[72:73], v[16:17]
	s_nop 0
	v_addc_co_u32_e32 v55, vcc, 0, v79, vcc
	v_pk_fma_f32 v[50:51], v[80:81], v[70:71], v[14:15]
	global_store_dwordx4 v[54:55], v[70:73], off sc1
	s_nop 1
	v_mov_b64_e32 v[72:73], v[52:53]
	v_mov_b64_e32 v[70:71], v[50:51]
	s_and_b64 vcc, exec, s[2:3]
	s_cbranch_vccnz .LBB0_806
.LBB0_831:
	v_mov_b32_e32 v50, v80
	v_mov_b32_e32 v51, v80
	v_add_co_u32_e32 v54, vcc, 0x340000, v78
	v_pk_fma_f32 v[52:53], v[50:51], v[72:73], v[12:13]
	s_nop 0
	v_addc_co_u32_e32 v55, vcc, 0, v79, vcc
	v_pk_fma_f32 v[50:51], v[80:81], v[70:71], v[10:11]
	global_store_dwordx4 v[54:55], v[70:73], off sc1
	s_nop 1
	v_mov_b64_e32 v[72:73], v[52:53]
	v_mov_b64_e32 v[70:71], v[50:51]
	s_and_b64 vcc, exec, s[2:3]
	s_cbranch_vccnz .LBB0_807
.LBB0_832:
	v_mov_b32_e32 v50, v80
	v_mov_b32_e32 v51, v80
	v_add_co_u32_e32 v54, vcc, 0x380000, v78
	v_pk_fma_f32 v[52:53], v[50:51], v[72:73], v[8:9]
	s_nop 0
	v_addc_co_u32_e32 v55, vcc, 0, v79, vcc
	v_pk_fma_f32 v[50:51], v[80:81], v[70:71], v[6:7]
	global_store_dwordx4 v[54:55], v[70:73], off sc1
	s_nop 1
	v_mov_b64_e32 v[72:73], v[52:53]
	v_mov_b64_e32 v[70:71], v[50:51]
	s_and_b64 vcc, exec, s[2:3]
	s_cbranch_vccz .LBB0_808
	s_branch .LBB0_809
